# FFN-in GEMM main loop: LDS-DMA with SGPR base + 32-bit lane offset instead of a 64-bit VALU add per DMA
# speedup vs baseline: 1.0031x; 1.0031x over previous
.LBB0_678:
	ds_read_b128 v[96:99], v171
	ds_read_b128 v[100:103], v171 offset:1024
	ds_read_b128 v[104:107], v171 offset:2048
	ds_read_b128 v[108:111], v171 offset:3072
	ds_read_b128 v[164:167], v172
	ds_read_b128 v[176:179], v172 offset:1024
	ds_read_b128 v[180:183], v172 offset:2048
	ds_read_b128 v[184:187], v172 offset:3072
	s_add_u32 s30, s28, 0xfffc0080
	s_addc_u32 s31, s29, -1
	s_cmp_eq_u32 s61, 12
	s_cselect_b32 s35, s1, s31
	s_cselect_b32 s34, s23, s30
	s_cselect_b32 s31, s21, s60
	s_cselect_b32 s30, s38, s39
	s_add_i32 m0, s44, 0xc000
	ds_read_b128 v[190:193], v173
	ds_read_b128 v[194:197], v173 offset:1024
	ds_read_b128 v[198:201], v173 offset:2048
	ds_read_b128 v[202:205], v173 offset:3072
	ds_read_b128 v[206:209], v173 offset:4096
	ds_read_b128 v[210:213], v173 offset:5120
	ds_read_b128 v[214:217], v173 offset:6144
	ds_read_b128 v[218:221], v173 offset:7168
	global_load_lds_dwordx4 v156, s[28:29]
	s_add_i32 m0, s44, 0xe000
	s_nop 0
	global_load_lds_dwordx4 v158, s[28:29]
	s_waitcnt vmcnt(8)
	s_waitcnt lgkmcnt(0)
	s_barrier
	s_setprio 1
	s_waitcnt lgkmcnt(0)
	v_mfma_f32_16x16x32_bf16 v[140:143], v[96:99], v[190:193], v[140:143]
	v_mfma_f32_16x16x32_bf16 v[136:139], v[104:107], v[190:193], v[136:139]
	v_mfma_f32_16x16x32_bf16 v[124:127], v[96:99], v[198:201], v[124:127]
	v_mfma_f32_16x16x32_bf16 v[120:123], v[104:107], v[198:201], v[120:123]
	v_mfma_f32_16x16x32_bf16 v[92:95], v[96:99], v[206:209], v[92:95]
	v_mfma_f32_16x16x32_bf16 v[88:91], v[104:107], v[206:209], v[88:91]
	v_mfma_f32_16x16x32_bf16 v[76:79], v[96:99], v[214:217], v[76:79]
	v_mfma_f32_16x16x32_bf16 v[72:75], v[104:107], v[214:217], v[72:75]
	v_mfma_f32_16x16x32_bf16 v[140:143], v[100:103], v[194:197], v[140:143]
	v_mfma_f32_16x16x32_bf16 v[136:139], v[108:111], v[194:197], v[136:139]
	v_mfma_f32_16x16x32_bf16 v[124:127], v[100:103], v[202:205], v[124:127]
	v_mfma_f32_16x16x32_bf16 v[120:123], v[108:111], v[202:205], v[120:123]
	v_mfma_f32_16x16x32_bf16 v[92:95], v[100:103], v[210:213], v[92:95]
	v_mfma_f32_16x16x32_bf16 v[88:91], v[108:111], v[210:213], v[88:91]
	v_mfma_f32_16x16x32_bf16 v[76:79], v[100:103], v[218:221], v[76:79]
	v_mfma_f32_16x16x32_bf16 v[72:75], v[108:111], v[218:221], v[72:75]
	s_setprio 0
	s_setprio 1
	v_mfma_f32_16x16x32_bf16 v[132:135], v[164:167], v[190:193], v[132:135]
	v_mfma_f32_16x16x32_bf16 v[128:131], v[180:183], v[190:193], v[128:131]
	v_mfma_f32_16x16x32_bf16 v[116:119], v[164:167], v[198:201], v[116:119]
	v_mfma_f32_16x16x32_bf16 v[112:115], v[180:183], v[198:201], v[112:115]
	v_mfma_f32_16x16x32_bf16 v[84:87], v[164:167], v[206:209], v[84:87]
	v_mfma_f32_16x16x32_bf16 v[80:83], v[180:183], v[206:209], v[80:83]
	v_mfma_f32_16x16x32_bf16 v[68:71], v[164:167], v[214:217], v[68:71]
	v_mfma_f32_16x16x32_bf16 v[64:67], v[180:183], v[214:217], v[64:67]
	v_mfma_f32_16x16x32_bf16 v[132:135], v[176:179], v[194:197], v[132:135]
	v_mfma_f32_16x16x32_bf16 v[128:131], v[184:187], v[194:197], v[128:131]
	v_mfma_f32_16x16x32_bf16 v[116:119], v[176:179], v[202:205], v[116:119]
	v_mfma_f32_16x16x32_bf16 v[112:115], v[184:187], v[202:205], v[112:115]
	v_mfma_f32_16x16x32_bf16 v[84:87], v[176:179], v[210:213], v[84:87]
	v_mfma_f32_16x16x32_bf16 v[80:83], v[184:187], v[210:213], v[80:83]
	v_mfma_f32_16x16x32_bf16 v[68:71], v[176:179], v[218:221], v[68:71]
	v_mfma_f32_16x16x32_bf16 v[64:67], v[184:187], v[218:221], v[64:67]
	s_setprio 0
	s_barrier
	s_add_i32 s62, s55, s41
	s_mov_b32 m0, s62
	ds_read_b128 v[190:193], v173 offset:16384
	ds_read_b128 v[194:197], v173 offset:17408
	ds_read_b128 v[198:201], v173 offset:18432
	ds_read_b128 v[202:205], v173 offset:19456
	ds_read_b128 v[206:209], v173 offset:20480
	ds_read_b128 v[210:213], v173 offset:21504
	ds_read_b128 v[214:217], v173 offset:22528
	ds_read_b128 v[218:221], v173 offset:23552
	global_load_lds_dwordx4 v148, s[30:31]
	s_add_i32 m0, s62, 0x2000
	s_add_u32 s62, s30, 0x40000
	s_addc_u32 s63, s31, 0
	s_add_i32 s64, s56, s41
	global_load_lds_dwordx4 v144, s[30:31]
	s_mov_b32 m0, s64
	s_nop 0
	global_load_lds_dwordx4 v148, s[62:63]
	s_add_i32 m0, s64, 0x2000
	s_nop 0
	global_load_lds_dwordx4 v144, s[62:63]
	s_add_u32 s100, s34, s14
	s_addc_u32 s101, s35, s15
	s_mov_b32 m0, s44
	s_nop 0
	global_load_lds_dwordx4 v150, s[34:35]
	s_mov_b32 m0, s45
	s_nop 0
	global_load_lds_dwordx4 v146, s[34:35]
	s_waitcnt vmcnt(8)
	s_waitcnt lgkmcnt(0)
	s_barrier
	s_setprio 1
	s_waitcnt lgkmcnt(0)
	v_mfma_f32_16x16x32_bf16 v[60:63], v[96:99], v[190:193], v[60:63]
	v_mfma_f32_16x16x32_bf16 v[56:59], v[104:107], v[190:193], v[56:59]
	v_mfma_f32_16x16x32_bf16 v[44:47], v[96:99], v[198:201], v[44:47]
	v_mfma_f32_16x16x32_bf16 v[40:43], v[104:107], v[198:201], v[40:43]
	v_mfma_f32_16x16x32_bf16 v[28:31], v[96:99], v[206:209], v[28:31]
	v_mfma_f32_16x16x32_bf16 v[24:27], v[104:107], v[206:209], v[24:27]
	v_mfma_f32_16x16x32_bf16 v[12:15], v[96:99], v[214:217], v[12:15]
	v_mfma_f32_16x16x32_bf16 v[8:11], v[104:107], v[214:217], v[8:11]
	v_mfma_f32_16x16x32_bf16 v[60:63], v[100:103], v[194:197], v[60:63]
	v_mfma_f32_16x16x32_bf16 v[56:59], v[108:111], v[194:197], v[56:59]
	v_mfma_f32_16x16x32_bf16 v[44:47], v[100:103], v[202:205], v[44:47]
	v_mfma_f32_16x16x32_bf16 v[40:43], v[108:111], v[202:205], v[40:43]
	v_mfma_f32_16x16x32_bf16 v[28:31], v[100:103], v[210:213], v[28:31]
	v_mfma_f32_16x16x32_bf16 v[24:27], v[108:111], v[210:213], v[24:27]
	v_mfma_f32_16x16x32_bf16 v[12:15], v[100:103], v[218:221], v[12:15]
	v_mfma_f32_16x16x32_bf16 v[8:11], v[108:111], v[218:221], v[8:11]
	s_setprio 0
	s_setprio 1
	v_mfma_f32_16x16x32_bf16 v[52:55], v[164:167], v[190:193], v[52:55]
	v_mfma_f32_16x16x32_bf16 v[48:51], v[180:183], v[190:193], v[48:51]
	v_mfma_f32_16x16x32_bf16 v[36:39], v[164:167], v[198:201], v[36:39]
	v_mfma_f32_16x16x32_bf16 v[32:35], v[180:183], v[198:201], v[32:35]
	v_mfma_f32_16x16x32_bf16 v[20:23], v[164:167], v[206:209], v[20:23]
	v_mfma_f32_16x16x32_bf16 v[16:19], v[180:183], v[206:209], v[16:19]
	v_mfma_f32_16x16x32_bf16 v[4:7], v[164:167], v[214:217], v[4:7]
	v_mfma_f32_16x16x32_bf16 v[0:3], v[180:183], v[214:217], v[0:3]
	v_mfma_f32_16x16x32_bf16 v[52:55], v[176:179], v[194:197], v[52:55]
	v_mfma_f32_16x16x32_bf16 v[48:51], v[184:187], v[194:197], v[48:51]
	v_mfma_f32_16x16x32_bf16 v[36:39], v[176:179], v[202:205], v[36:39]
	v_mfma_f32_16x16x32_bf16 v[32:35], v[184:187], v[202:205], v[32:35]
	v_mfma_f32_16x16x32_bf16 v[20:23], v[176:179], v[210:213], v[20:23]
	v_mfma_f32_16x16x32_bf16 v[16:19], v[184:187], v[210:213], v[16:19]
	v_mfma_f32_16x16x32_bf16 v[4:7], v[176:179], v[218:221], v[4:7]
	v_mfma_f32_16x16x32_bf16 v[0:3], v[184:187], v[218:221], v[0:3]
	s_setprio 0
	s_barrier
	s_add_i32 s62, 0, 0x18000
	s_add_i32 s63, 0, 0x1c000
	v_add_u32_e32 v108, s62, v170
	v_add_u32_e32 v152, s63, v170
	ds_read_b128 v[96:99], v108
	ds_read_b128 v[100:103], v108 offset:1024
	ds_read_b128 v[104:107], v108 offset:2048
	ds_read_b128 v[108:111], v108 offset:3072
	ds_read_b128 v[164:167], v152
	ds_read_b128 v[176:179], v152 offset:1024
	ds_read_b128 v[180:183], v152 offset:2048
	ds_read_b128 v[184:187], v152 offset:3072
	s_add_u32 s34, s34, 0x40000
	s_addc_u32 s35, s35, 0
	s_mov_b32 m0, s46
	ds_read_b128 v[190:193], v173 offset:32768
	ds_read_b128 v[194:197], v173 offset:33792
	ds_read_b128 v[198:201], v173 offset:34816
	ds_read_b128 v[202:205], v173 offset:35840
	ds_read_b128 v[206:209], v173 offset:36864
	ds_read_b128 v[210:213], v173 offset:37888
	ds_read_b128 v[214:217], v173 offset:38912
	ds_read_b128 v[218:221], v173 offset:39936
	global_load_lds_dwordx4 v150, s[34:35]
	s_mov_b32 m0, s47
	s_nop 0
	global_load_lds_dwordx4 v146, s[34:35]
	s_waitcnt vmcnt(8)
	s_waitcnt lgkmcnt(0)
	s_barrier
	s_setprio 1
	s_waitcnt lgkmcnt(0)
	v_mfma_f32_16x16x32_bf16 v[140:143], v[96:99], v[190:193], v[140:143]
	v_mfma_f32_16x16x32_bf16 v[136:139], v[104:107], v[190:193], v[136:139]
	v_mfma_f32_16x16x32_bf16 v[124:127], v[96:99], v[198:201], v[124:127]
	v_mfma_f32_16x16x32_bf16 v[120:123], v[104:107], v[198:201], v[120:123]
	v_mfma_f32_16x16x32_bf16 v[92:95], v[96:99], v[206:209], v[92:95]
	v_mfma_f32_16x16x32_bf16 v[88:91], v[104:107], v[206:209], v[88:91]
	v_mfma_f32_16x16x32_bf16 v[76:79], v[96:99], v[214:217], v[76:79]
	v_mfma_f32_16x16x32_bf16 v[72:75], v[104:107], v[214:217], v[72:75]
	v_mfma_f32_16x16x32_bf16 v[140:143], v[100:103], v[194:197], v[140:143]
	v_mfma_f32_16x16x32_bf16 v[136:139], v[108:111], v[194:197], v[136:139]
	v_mfma_f32_16x16x32_bf16 v[124:127], v[100:103], v[202:205], v[124:127]
	v_mfma_f32_16x16x32_bf16 v[120:123], v[108:111], v[202:205], v[120:123]
	v_mfma_f32_16x16x32_bf16 v[92:95], v[100:103], v[210:213], v[92:95]
	v_mfma_f32_16x16x32_bf16 v[88:91], v[108:111], v[210:213], v[88:91]
	v_mfma_f32_16x16x32_bf16 v[76:79], v[100:103], v[218:221], v[76:79]
	v_mfma_f32_16x16x32_bf16 v[72:75], v[108:111], v[218:221], v[72:75]
	s_setprio 0
	s_setprio 1
	v_mfma_f32_16x16x32_bf16 v[132:135], v[164:167], v[190:193], v[132:135]
	v_mfma_f32_16x16x32_bf16 v[128:131], v[180:183], v[190:193], v[128:131]
	v_mfma_f32_16x16x32_bf16 v[116:119], v[164:167], v[198:201], v[116:119]
	v_mfma_f32_16x16x32_bf16 v[112:115], v[180:183], v[198:201], v[112:115]
	v_mfma_f32_16x16x32_bf16 v[84:87], v[164:167], v[206:209], v[84:87]
	v_mfma_f32_16x16x32_bf16 v[80:83], v[180:183], v[206:209], v[80:83]
	v_mfma_f32_16x16x32_bf16 v[68:71], v[164:167], v[214:217], v[68:71]
	v_mfma_f32_16x16x32_bf16 v[64:67], v[180:183], v[214:217], v[64:67]
	v_mfma_f32_16x16x32_bf16 v[132:135], v[176:179], v[194:197], v[132:135]
	v_mfma_f32_16x16x32_bf16 v[128:131], v[184:187], v[194:197], v[128:131]
	v_mfma_f32_16x16x32_bf16 v[116:119], v[176:179], v[202:205], v[116:119]
	v_mfma_f32_16x16x32_bf16 v[112:115], v[184:187], v[202:205], v[112:115]
	v_mfma_f32_16x16x32_bf16 v[84:87], v[176:179], v[210:213], v[84:87]
	v_mfma_f32_16x16x32_bf16 v[80:83], v[184:187], v[210:213], v[80:83]
	v_mfma_f32_16x16x32_bf16 v[68:71], v[176:179], v[218:221], v[68:71]
	v_mfma_f32_16x16x32_bf16 v[64:67], v[184:187], v[218:221], v[64:67]
	s_setprio 0
	s_barrier
	s_add_i32 s34, s62, s41
	s_add_u32 s98, s30, s14
	s_addc_u32 s99, s31, s15
	s_mov_b32 m0, s34
	ds_read_b128 v[190:193], v173 offset:49152
	ds_read_b128 v[194:197], v173 offset:50176
	ds_read_b128 v[198:201], v173 offset:51200
	ds_read_b128 v[202:205], v173 offset:52224
	ds_read_b128 v[206:209], v173 offset:53248
	ds_read_b128 v[210:213], v173 offset:54272
	ds_read_b128 v[214:217], v173 offset:55296
	ds_read_b128 v[218:221], v173 offset:56320
	global_load_lds_dwordx4 v148, s[98:99]
	s_add_i32 m0, s34, 0x2000
	s_add_u32 s30, s30, 0x40080
	s_addc_u32 s31, s31, 0
	s_add_i32 s34, s63, s41
	global_load_lds_dwordx4 v144, s[98:99]
	s_mov_b32 m0, s34
	s_nop 0
	global_load_lds_dwordx4 v148, s[30:31]
	s_add_i32 m0, s34, 0x2000
	s_nop 0
	global_load_lds_dwordx4 v144, s[30:31]
	s_mov_b32 m0, s51
	s_nop 0
	global_load_lds_dwordx4 v150, s[100:101]
	s_mov_b32 m0, s52
	s_nop 0
	global_load_lds_dwordx4 v146, s[100:101]
	s_waitcnt vmcnt(8)
	s_waitcnt lgkmcnt(0)
	s_barrier
	s_setprio 1
	s_waitcnt lgkmcnt(0)
	v_mfma_f32_16x16x32_bf16 v[60:63], v[96:99], v[190:193], v[60:63]
	v_mfma_f32_16x16x32_bf16 v[56:59], v[104:107], v[190:193], v[56:59]
	v_mfma_f32_16x16x32_bf16 v[44:47], v[96:99], v[198:201], v[44:47]
	v_mfma_f32_16x16x32_bf16 v[40:43], v[104:107], v[198:201], v[40:43]
	v_mfma_f32_16x16x32_bf16 v[28:31], v[96:99], v[206:209], v[28:31]
	v_mfma_f32_16x16x32_bf16 v[24:27], v[104:107], v[206:209], v[24:27]
	v_mfma_f32_16x16x32_bf16 v[12:15], v[96:99], v[214:217], v[12:15]
	v_mfma_f32_16x16x32_bf16 v[8:11], v[104:107], v[214:217], v[8:11]
	v_mfma_f32_16x16x32_bf16 v[60:63], v[100:103], v[194:197], v[60:63]
	v_mfma_f32_16x16x32_bf16 v[56:59], v[108:111], v[194:197], v[56:59]
	v_mfma_f32_16x16x32_bf16 v[44:47], v[100:103], v[202:205], v[44:47]
	v_mfma_f32_16x16x32_bf16 v[40:43], v[108:111], v[202:205], v[40:43]
	v_mfma_f32_16x16x32_bf16 v[28:31], v[100:103], v[210:213], v[28:31]
	v_mfma_f32_16x16x32_bf16 v[24:27], v[108:111], v[210:213], v[24:27]
	v_mfma_f32_16x16x32_bf16 v[12:15], v[100:103], v[218:221], v[12:15]
	v_mfma_f32_16x16x32_bf16 v[8:11], v[108:111], v[218:221], v[8:11]
	s_setprio 0
	s_setprio 1
	v_mfma_f32_16x16x32_bf16 v[52:55], v[164:167], v[190:193], v[52:55]
	v_mfma_f32_16x16x32_bf16 v[48:51], v[180:183], v[190:193], v[48:51]
	v_mfma_f32_16x16x32_bf16 v[36:39], v[164:167], v[198:201], v[36:39]
	v_mfma_f32_16x16x32_bf16 v[32:35], v[180:183], v[198:201], v[32:35]
	v_mfma_f32_16x16x32_bf16 v[20:23], v[164:167], v[206:209], v[20:23]
	v_mfma_f32_16x16x32_bf16 v[16:19], v[180:183], v[206:209], v[16:19]
	v_mfma_f32_16x16x32_bf16 v[4:7], v[164:167], v[214:217], v[4:7]
	v_mfma_f32_16x16x32_bf16 v[0:3], v[180:183], v[214:217], v[0:3]
	v_mfma_f32_16x16x32_bf16 v[52:55], v[176:179], v[194:197], v[52:55]
	v_mfma_f32_16x16x32_bf16 v[48:51], v[184:187], v[194:197], v[48:51]
	v_mfma_f32_16x16x32_bf16 v[36:39], v[176:179], v[202:205], v[36:39]
	v_mfma_f32_16x16x32_bf16 v[32:35], v[184:187], v[202:205], v[32:35]
	v_mfma_f32_16x16x32_bf16 v[20:23], v[176:179], v[210:213], v[20:23]
	v_mfma_f32_16x16x32_bf16 v[16:19], v[184:187], v[210:213], v[16:19]
	v_mfma_f32_16x16x32_bf16 v[4:7], v[176:179], v[218:221], v[4:7]
	v_mfma_f32_16x16x32_bf16 v[0:3], v[184:187], v[218:221], v[0:3]
	s_setprio 0
	s_barrier
	s_add_i32 s61, s61, 2
	s_add_u32 s28, s28, 0x100
	s_addc_u32 s29, s29, 0
	s_add_u32 s39, s39, 0x100
	s_addc_u32 s60, s60, 0
	s_cmp_gt_u32 s61, 13
	s_cbranch_scc0 .LBB0_678
	s_and_b64 vcc, exec, s[16:17]
	s_cbranch_vccz .LBB0_681
	s_barrier
